# c11 plus: spatial Ws restage loads batched; K/V window copy issues both loads before one wait
# speedup vs baseline: 1.0012x; 1.0012x over previous
.LBB0_705:
	s_ashr_i32 s4, s27, 3
	s_lshl_b32 s43, s4, 7
	v_add_u32_e32 v0, s43, v128
	v_ashrrev_i32_e32 v1, 31, v0
	v_lshlrev_b64 v[0:1], 8, v[0:1]
	v_lshl_add_u64 v[0:1], v[100:101], 0, v[0:1]
	global_load_dwordx4 v[44:47], v[0:1], off offset:48
	global_load_dwordx4 v[48:51], v[0:1], off offset:32
	global_load_dwordx4 v[56:59], v[0:1], off offset:16
	global_load_dwordx4 v[60:63], v[0:1], off
	v_add_u32_e32 v0, s43, v129
	v_ashrrev_i32_e32 v1, 31, v0
	s_and_b32 s44, s27, 7
	v_lshlrev_b64 v[0:1], 13, v[0:1]
	v_add_u32_e32 v2, s43, v130
	v_lshl_add_u64 v[0:1], s[8:9], 0, v[0:1]
	s_lshl_b32 s30, s44, 9
	v_ashrrev_i32_e32 v3, 31, v2
	v_lshl_add_u64 v[0:1], v[0:1], 0, s[30:31]
	v_mov_b32_e32 v111, v145
	v_lshlrev_b64 v[2:3], 13, v[2:3]
	v_lshl_add_u64 v[0:1], v[0:1], 0, v[110:111]
	v_lshl_add_u64 v[2:3], s[8:9], 0, v[2:3]
	v_add_co_u32_e32 v0, vcc, s72, v0
	v_lshl_add_u64 v[2:3], v[2:3], 0, s[30:31]
	s_nop 0
	v_addc_co_u32_e32 v1, vcc, 0, v1, vcc
	v_lshl_add_u64 v[2:3], v[2:3], 0, v[110:111]
	v_add_co_u32_e32 v2, vcc, s72, v2
	v_or_b32_e32 v114, s43, v118
	s_nop 0
	v_addc_co_u32_e32 v3, vcc, 0, v3, vcc
	global_load_dwordx4 v[76:79], v[0:1], off
	global_load_dwordx4 v[72:75], v[2:3], off
	v_add_u32_e32 v0, s43, v131
	v_ashrrev_i32_e32 v1, 31, v0
	v_lshlrev_b64 v[0:1], 13, v[0:1]
	v_add_u32_e32 v2, s43, v132
	v_lshl_add_u64 v[0:1], s[8:9], 0, v[0:1]
	v_ashrrev_i32_e32 v3, 31, v2
	v_lshl_add_u64 v[0:1], v[0:1], 0, s[30:31]
	v_lshlrev_b64 v[2:3], 13, v[2:3]
	v_lshl_add_u64 v[0:1], v[0:1], 0, v[110:111]
	v_lshl_add_u64 v[2:3], s[8:9], 0, v[2:3]
	v_add_co_u32_e32 v0, vcc, s72, v0
	v_lshl_add_u64 v[2:3], v[2:3], 0, s[30:31]
	s_nop 0
	v_addc_co_u32_e32 v1, vcc, 0, v1, vcc
	v_lshl_add_u64 v[2:3], v[2:3], 0, v[110:111]
	v_add_co_u32_e32 v2, vcc, s72, v2
	v_or_b32_e32 v4, 16, v114
	s_nop 0
	v_addc_co_u32_e32 v3, vcc, 0, v3, vcc
	global_load_dwordx4 v[68:71], v[0:1], off
	global_load_dwordx4 v[64:67], v[2:3], off
	v_add_u32_e32 v0, s43, v133
	v_ashrrev_i32_e32 v1, 31, v0
	v_lshlrev_b64 v[0:1], 13, v[0:1]
	v_add_u32_e32 v2, s43, v134
	v_lshl_add_u64 v[0:1], s[8:9], 0, v[0:1]
	v_ashrrev_i32_e32 v3, 31, v2
	v_lshl_add_u64 v[0:1], v[0:1], 0, s[30:31]
	v_lshlrev_b64 v[2:3], 13, v[2:3]
	v_lshl_add_u64 v[0:1], v[0:1], 0, v[110:111]
	v_lshl_add_u64 v[2:3], s[8:9], 0, v[2:3]
	v_add_co_u32_e32 v0, vcc, s72, v0
	v_lshl_add_u64 v[2:3], v[2:3], 0, s[30:31]
	s_nop 0
	v_addc_co_u32_e32 v1, vcc, 0, v1, vcc
	v_lshl_add_u64 v[2:3], v[2:3], 0, v[110:111]
	v_add_co_u32_e32 v2, vcc, s72, v2
	v_ashrrev_i32_e32 v115, 31, v114
	s_nop 0
	v_addc_co_u32_e32 v3, vcc, 0, v3, vcc
	global_load_dwordx4 v[52:55], v[0:1], off
	global_load_dwordx4 v[40:43], v[2:3], off
	v_add_u32_e32 v0, s43, v135
	v_ashrrev_i32_e32 v1, 31, v0
	v_lshlrev_b64 v[0:1], 13, v[0:1]
	v_add_u32_e32 v2, s43, v136
	v_lshl_add_u64 v[0:1], s[8:9], 0, v[0:1]
	v_ashrrev_i32_e32 v3, 31, v2
	v_lshl_add_u64 v[0:1], v[0:1], 0, s[30:31]
	v_lshlrev_b64 v[2:3], 13, v[2:3]
	v_lshl_add_u64 v[0:1], v[0:1], 0, v[110:111]
	v_lshl_add_u64 v[2:3], s[8:9], 0, v[2:3]
	v_add_co_u32_e32 v0, vcc, s72, v0
	v_lshl_add_u64 v[2:3], v[2:3], 0, s[30:31]
	s_nop 0
	v_addc_co_u32_e32 v1, vcc, 0, v1, vcc
	v_lshl_add_u64 v[2:3], v[2:3], 0, v[110:111]
	v_add_co_u32_e32 v2, vcc, s72, v2
	v_ashrrev_i32_e32 v5, 31, v4
	s_nop 0
	v_addc_co_u32_e32 v3, vcc, 0, v3, vcc
	global_load_dwordx4 v[36:39], v[0:1], off
	global_load_dwordx4 v[32:35], v[2:3], off
	v_lshl_add_u64 v[0:1], v[96:97], 0, s[30:31]
	v_lshlrev_b64 v[2:3], 13, v[114:115]
	v_lshlrev_b64 v[4:5], 13, v[4:5]
	v_lshl_add_u64 v[2:3], v[0:1], 0, v[2:3]
	v_lshl_add_u64 v[4:5], v[0:1], 0, v[4:5]
	global_load_dwordx4 v[28:31], v[2:3], off
	global_load_dwordx4 v[24:27], v[4:5], off
	v_or_b32_e32 v2, 32, v114
	v_or_b32_e32 v4, 48, v114
	v_ashrrev_i32_e32 v3, 31, v2
	v_ashrrev_i32_e32 v5, 31, v4
	v_lshlrev_b64 v[2:3], 13, v[2:3]
	v_lshlrev_b64 v[4:5], 13, v[4:5]
	v_lshl_add_u64 v[2:3], v[0:1], 0, v[2:3]
	v_lshl_add_u64 v[4:5], v[0:1], 0, v[4:5]
	global_load_dwordx4 v[20:23], v[2:3], off
	global_load_dwordx4 v[16:19], v[4:5], off
	v_or_b32_e32 v2, 64, v114
	v_or_b32_e32 v4, 0x50, v114
	v_ashrrev_i32_e32 v3, 31, v2
	v_ashrrev_i32_e32 v5, 31, v4
	v_lshlrev_b64 v[2:3], 13, v[2:3]
	v_lshlrev_b64 v[4:5], 13, v[4:5]
	v_lshl_add_u64 v[2:3], v[0:1], 0, v[2:3]
	v_lshl_add_u64 v[4:5], v[0:1], 0, v[4:5]
	global_load_dwordx4 v[12:15], v[2:3], off
	global_load_dwordx4 v[8:11], v[4:5], off
	v_or_b32_e32 v2, 0x60, v114
	v_or_b32_e32 v4, 0x70, v114
	v_ashrrev_i32_e32 v3, 31, v2
	v_ashrrev_i32_e32 v5, 31, v4
	v_lshlrev_b64 v[2:3], 13, v[2:3]
	v_lshlrev_b64 v[4:5], 13, v[4:5]
	v_lshl_add_u64 v[2:3], v[0:1], 0, v[2:3]
	v_lshl_add_u64 v[0:1], v[0:1], 0, v[4:5]
	global_load_dwordx4 v[4:7], v[2:3], off
	s_nop 0
	global_load_dwordx4 v[0:3], v[0:1], off
	s_cmpk_gt_i32 s4, 0x7f
	s_cselect_b64 s[40:41], -1, 0
	s_and_b64 s[4:5], s[40:41], exec
	s_cselect_b32 s4, 8, 0
	s_or_b32 s4, s4, s44
	s_cmp_eq_u32 s42, s4
	s_cbranch_scc1 .LBB0_707
	s_lshl_b32 s5, s4, 15
	s_add_u32 s38, s15, s5
	s_addc_u32 s39, s26, 0
	v_lshl_add_u64 v[80:81], s[38:39], 0, v[102:103]
	v_mov_b32_e32 v113, v145
	v_lshl_add_u64 v[80:81], v[80:81], 0, v[112:113]
	global_load_dwordx4 v[216:219], v[80:81], off
	s_mov_b32 s42, s4
	v_lshl_add_u64 v[80:81], s[38:39], 0, v[104:105]
	v_lshl_add_u64 v[80:81], v[80:81], 0, v[112:113]
	global_load_dwordx4 v[220:223], v[80:81], off
	v_lshl_add_u64 v[80:81], s[38:39], 0, v[106:107]
	v_lshl_add_u64 v[80:81], v[80:81], 0, v[112:113]
	global_load_dwordx4 v[224:227], v[80:81], off
	v_lshl_add_u64 v[80:81], s[38:39], 0, v[108:109]
	v_lshl_add_u64 v[80:81], v[80:81], 0, v[112:113]
	global_load_dwordx4 v[228:231], v[80:81], off
	s_waitcnt vmcnt(0)
	ds_write_b128 v165, v[216:219]
	ds_write_b128 v166, v[220:223]
	ds_write_b128 v167, v[224:227]
	ds_write_b128 v168, v[228:231]

.LBB0_850:
	s_mov_b64 s[16:17], s[0:1]
	s_load_dwordx2 s[16:17], s[16:17], 0x10
	v_mul_hi_u32 v1, v0, s71
	v_mul_hi_u32 v2, v34, s71
	v_lshrrev_b32_e32 v1, 13, v1
	v_lshlrev_b32_e32 v2, 3, v2
	v_mul_u32_u24_e32 v1, 0x3c00, v1
	v_and_b32_e32 v144, 0xffffc000, v2
	v_sub_u32_e32 v1, v0, v1
	s_waitcnt vmcnt(2)
	v_lshlrev_b64 v[6:7], 2, v[144:145]
	v_lshlrev_b32_e32 v144, 2, v1
	s_waitcnt lgkmcnt(0)
	v_lshl_add_u64 v[2:3], s[16:17], 0, v[6:7]
	v_lshl_add_u64 v[2:3], v[2:3], 0, v[144:145]
	v_add_co_u32_e32 v2, vcc, s72, v2
	v_lshl_add_u64 v[8:9], s[60:61], 0, v[6:7]
	s_nop 0
	v_addc_co_u32_e32 v3, vcc, 0, v3, vcc
	global_load_dwordx4 v[2:5], v[2:3], off
	s_mov_b64 s[16:17], s[0:1]
	s_load_dwordx2 s[16:17], s[16:17], 0x18
	v_lshl_add_u64 v[8:9], v[8:9], 0, v[144:145]
	v_lshl_add_u64 v[34:35], v[34:35], 0, s[8:9]
	v_add_u32_e32 v0, s12, v0
	s_waitcnt lgkmcnt(0)
	v_lshl_add_u64 v[10:11], s[16:17], 0, v[6:7]
	v_lshl_add_u64 v[10:11], v[10:11], 0, v[144:145]
	v_add_co_u32_e32 v10, vcc, 0x1000, v10
	s_mov_b64 s[16:17], 0x77fff
	s_nop 0
	v_addc_co_u32_e32 v11, vcc, 0, v11, vcc
	global_load_dwordx4 v[10:13], v[10:11], off
	v_cmp_lt_u64_e32 vcc, s[16:17], v[34:35]
	v_lshl_add_u64 v[6:7], s[62:63], 0, v[6:7]
	s_or_b64 s[10:11], vcc, s[10:11]
	v_lshl_add_u64 v[6:7], v[6:7], 0, v[144:145]
	s_waitcnt vmcnt(0)
	global_store_dwordx4 v[8:9], v[2:5], off
	global_store_dwordx4 v[6:7], v[10:13], off
	s_andn2_b64 exec, exec, s[10:11]
	s_cbranch_execnz .LBB0_850
